# non-leader workgroups poll the cross-XCD release word directly instead of the per-XCD generation word
# speedup vs baseline: 1.0180x; 1.0057x over previous
.LBB0_819:
	s_or_b64 exec, exec, s[12:13]
	v_cvt_f32_u32_e32 v5, v3
	s_waitcnt vmcnt(0)
	v_readfirstlane_b32 s0, v4
	v_sub_u32_e32 v4, 0, v3
	v_rcp_iflag_f32_e32 v5, v5
	v_add_u32_e32 v6, s0, v2
	v_mul_f32_e32 v5, 0x4f7ffffe, v5
	v_cvt_u32_f32_e32 v5, v5
	v_mul_lo_u32 v2, v4, v5
	v_mul_hi_u32 v2, v5, v2
	v_add_u32_e32 v2, v5, v2
	v_mul_hi_u32 v2, v6, v2
	v_mul_lo_u32 v4, v2, v3
	v_sub_u32_e32 v4, v6, v4
	v_add_u32_e32 v5, 1, v2
	v_cmp_ge_u32_e32 vcc, v4, v3
	s_nop 1
	v_cndmask_b32_e32 v2, v2, v5, vcc
	v_sub_u32_e32 v5, v4, v3
	v_cndmask_b32_e32 v4, v4, v5, vcc
	v_add_u32_e32 v5, 1, v2
	v_cmp_ge_u32_e32 vcc, v4, v3
	v_add_u32_e32 v4, 1, v6
	s_nop 0
	v_cndmask_b32_e32 v2, v2, v5, vcc
	v_mul_lo_u32 v5, v3, v2
	v_add_u32_e32 v3, v5, v3
	v_cmp_ne_u32_e32 vcc, v4, v3
	s_and_saveexec_b64 s[0:1], vcc
	s_xor_b64 s[10:11], exec, s[0:1]
	s_cbranch_execz .LBB0_833
	s_waitcnt lgkmcnt(0)
	s_add_u32 s14, s78, 0x24703500
	s_addc_u32 s15, s79, 0
	global_load_dword v1, v0, s[14:15] sc1
	s_waitcnt vmcnt(0)
	v_cmp_eq_u32_e32 vcc, v1, v2
	s_and_saveexec_b64 s[12:13], vcc
	s_cbranch_execz .LBB0_832
	s_mov_b32 s0, 1
	s_mov_b64 s[16:17], 0
	s_branch .LBB0_823
